# attn inner loops: loop control rewritten (odd ntiles => one not-last test per trip; exact vmcnt at the LDS stores; ~35 fewer scalar/branch instrs per tile)
# speedup vs baseline: 1.0283x; 1.0211x over previous
.LBB0_836:
	s_add_i32 s88, s89, 2
	s_cmp_lt_u32 s88, s84
	s_cbranch_scc0 .Lq1_last
	v_add_co_u32_e32 v2, vcc, 0xfbf00000, v202
	s_nop 1
	v_addc_co_u32_e32 v3, vcc, -1, v203, vcc
	global_load_dwordx4 v[28:31], v[2:3], off offset:-128
	global_load_dwordx4 v[32:35], v[2:3], off
	v_add_co_u32_e32 v2, vcc, 0xffffc000, v202
	s_nop 1
	v_addc_co_u32_e32 v3, vcc, -1, v203, vcc
	global_load_dwordx4 v[4:7], v[2:3], off offset:-128
	global_load_dwordx4 v[12:15], v[2:3], off
	ds_read_b128 v[44:47], v214 offset:35840
	ds_read_b128 v[72:75], v214 offset:35904
	ds_read_b128 v[92:95], v214 offset:40192
	ds_read_b128 v[112:115], v214 offset:40256
	ds_read_b128 v[132:135], v214 offset:44544
	ds_read_b128 v[148:151], v214 offset:44608
	ds_read_b128 v[136:139], v214 offset:48896
	ds_read_b128 v[152:155], v214 offset:48960
	s_waitcnt lgkmcnt(7)
	v_mfma_f32_16x16x32_bf16 v[140:143], v[44:47], v[8:11], 0
	v_mfma_f32_16x16x32_bf16 v[44:47], v[44:47], v[20:23], 0
	s_waitcnt lgkmcnt(5)
	v_mfma_f32_16x16x32_bf16 v[156:159], v[92:95], v[8:11], 0
	v_mfma_f32_16x16x32_bf16 v[92:95], v[92:95], v[20:23], 0
	s_waitcnt lgkmcnt(3)
	v_mfma_f32_16x16x32_bf16 v[160:163], v[132:135], v[8:11], 0
	v_mfma_f32_16x16x32_bf16 v[132:135], v[132:135], v[20:23], 0
	s_waitcnt lgkmcnt(1)
	v_mfma_f32_16x16x32_bf16 v[164:167], v[136:139], v[8:11], 0
	v_mfma_f32_16x16x32_bf16 v[168:171], v[136:139], v[20:23], 0
	v_mfma_f32_16x16x32_bf16 v[144:147], v[72:75], v[16:19], v[140:143]
	v_mfma_f32_16x16x32_bf16 v[136:139], v[72:75], v[24:27], v[44:47]
	v_mfma_f32_16x16x32_bf16 v[44:47], v[112:115], v[16:19], v[156:159]
	v_mfma_f32_16x16x32_bf16 v[92:95], v[112:115], v[24:27], v[92:95]
	v_mfma_f32_16x16x32_bf16 v[140:143], v[148:151], v[16:19], v[160:163]
	v_mfma_f32_16x16x32_bf16 v[132:135], v[148:151], v[24:27], v[132:135]
	s_waitcnt lgkmcnt(0)
	v_mfma_f32_16x16x32_bf16 v[72:75], v[152:155], v[16:19], v[164:167]
	v_mfma_f32_16x16x32_bf16 v[112:115], v[152:155], v[24:27], v[168:171]
	v_cmp_neq_f32_e32 vcc, 0, v196
	v_cmp_neq_f32_e64 s[0:1], 0, v197
	s_or_b64 vcc, vcc, s[0:1]
	s_cbranch_vccz .LBB0_859
	v_sub_f32_e32 v147, v147, v196
	v_sub_f32_e32 v146, v146, v196
	v_sub_f32_e32 v145, v145, v196
	v_sub_f32_e32 v144, v144, v196
	v_sub_f32_e32 v47, v47, v196
	v_sub_f32_e32 v46, v46, v196
	v_sub_f32_e32 v45, v45, v196
	v_sub_f32_e32 v44, v44, v196
	v_sub_f32_e32 v143, v143, v196
	v_sub_f32_e32 v142, v142, v196
	v_sub_f32_e32 v141, v141, v196
	v_sub_f32_e32 v140, v140, v196
	v_sub_f32_e32 v75, v75, v196
	v_sub_f32_e32 v74, v74, v196
	v_sub_f32_e32 v73, v73, v196
	v_sub_f32_e32 v72, v72, v196
	v_sub_f32_e32 v139, v139, v197
	v_sub_f32_e32 v138, v138, v197
	v_sub_f32_e32 v137, v137, v197
	v_sub_f32_e32 v136, v136, v197
	v_sub_f32_e32 v95, v95, v197
	v_sub_f32_e32 v94, v94, v197
	v_sub_f32_e32 v93, v93, v197
	v_sub_f32_e32 v92, v92, v197
	v_sub_f32_e32 v135, v135, v197
	v_sub_f32_e32 v134, v134, v197
	v_sub_f32_e32 v133, v133, v197
	v_sub_f32_e32 v132, v132, v197
	v_sub_f32_e32 v115, v115, v197
	v_sub_f32_e32 v114, v114, v197
	v_sub_f32_e32 v113, v113, v197
	v_sub_f32_e32 v112, v112, v197

.LBB0_866:
	s_waitcnt vmcnt(3)
	ds_write_b128 v211, v[28:31]
	s_waitcnt vmcnt(2)
	ds_write_b128 v211, v[32:35] offset:128
	s_waitcnt vmcnt(1)
	ds_write_b128 v213, v[4:7] offset:53248
	s_waitcnt vmcnt(0)
	ds_write_b128 v213, v[12:15] offset:53376
	s_waitcnt lgkmcnt(0)
	s_barrier
	s_cmp_lt_u32 s89, s82
	s_cselect_b32 s99, 1, 0
	s_cbranch_scc0 .Lq1_h2_nok
	v_add_co_u32_e32 v2, vcc, 0xfbf04000, v202
	s_nop 1
	v_addc_co_u32_e32 v3, vcc, -1, v203, vcc
	global_load_dwordx4 v[28:31], v[2:3], off offset:-128
	global_load_dwordx4 v[32:35], v[2:3], off
.Lq1_h2_nok:
	global_load_dwordx4 v[4:7], v[202:203], off offset:-128
	global_load_dwordx4 v[12:15], v[202:203], off
	s_cmp_ge_u32 s89, s83
	s_cbranch_scc1 .Lq1_h2_pvonly
	ds_read_b128 v[36:39], v214
	ds_read_b128 v[40:43], v214 offset:64
	ds_read_b128 v[60:63], v214 offset:4352
	ds_read_b128 v[84:87], v214 offset:4416
	ds_read_b128 v[64:67], v214 offset:8704
	ds_read_b128 v[124:127], v214 offset:8768
	ds_read_b128 v[108:111], v214 offset:13056
	ds_read_b128 v[100:103], v214 offset:13120
	s_waitcnt lgkmcnt(7)
	v_mfma_f32_16x16x32_bf16 v[120:123], v[36:39], v[8:11], 0
	v_mfma_f32_16x16x32_bf16 v[36:39], v[36:39], v[20:23], 0
	s_waitcnt lgkmcnt(5)
	v_mfma_f32_16x16x32_bf16 v[116:119], v[60:63], v[8:11], 0
	v_mfma_f32_16x16x32_bf16 v[60:63], v[60:63], v[20:23], 0
	s_waitcnt lgkmcnt(3)
	v_mfma_f32_16x16x32_bf16 v[96:99], v[64:67], v[8:11], 0
	v_mfma_f32_16x16x32_bf16 v[64:67], v[64:67], v[20:23], 0
	s_waitcnt lgkmcnt(1)
	v_mfma_f32_16x16x32_bf16 v[104:107], v[108:111], v[8:11], 0
	v_mfma_f32_16x16x32_bf16 v[76:79], v[108:111], v[20:23], 0
	v_mfma_f32_16x16x32_bf16 v[128:131], v[40:43], v[16:19], v[120:123]
	v_mfma_f32_16x16x32_bf16 v[108:111], v[40:43], v[24:27], v[36:39]
	v_mfma_f32_16x16x32_bf16 v[36:39], v[84:87], v[16:19], v[116:119]
	v_mfma_f32_16x16x32_bf16 v[60:63], v[84:87], v[24:27], v[60:63]
	v_mfma_f32_16x16x32_bf16 v[120:123], v[124:127], v[16:19], v[96:99]
	v_mfma_f32_16x16x32_bf16 v[64:67], v[124:127], v[24:27], v[64:67]
	s_waitcnt lgkmcnt(0)
	v_mfma_f32_16x16x32_bf16 v[40:43], v[100:103], v[16:19], v[104:107]
	v_mfma_f32_16x16x32_bf16 v[84:87], v[100:103], v[24:27], v[76:79]
	v_cmp_neq_f32_e32 vcc, 0, v196
	v_cmp_neq_f32_e64 s[2:3], 0, v197
	s_or_b64 vcc, vcc, s[2:3]
	s_cbranch_vccz .LBB0_875
	v_sub_f32_e32 v131, v131, v196
	v_sub_f32_e32 v130, v130, v196
	v_sub_f32_e32 v129, v129, v196
	v_sub_f32_e32 v128, v128, v196
	v_sub_f32_e32 v39, v39, v196
	v_sub_f32_e32 v38, v38, v196
	v_sub_f32_e32 v37, v37, v196
	v_sub_f32_e32 v36, v36, v196
	v_sub_f32_e32 v123, v123, v196
	v_sub_f32_e32 v122, v122, v196
	v_sub_f32_e32 v121, v121, v196
	v_sub_f32_e32 v120, v120, v196
	v_sub_f32_e32 v43, v43, v196
	v_sub_f32_e32 v42, v42, v196
	v_sub_f32_e32 v41, v41, v196
	v_sub_f32_e32 v40, v40, v196
	v_sub_f32_e32 v111, v111, v197
	v_sub_f32_e32 v110, v110, v197
	v_sub_f32_e32 v109, v109, v197
	v_sub_f32_e32 v108, v108, v197
	v_sub_f32_e32 v63, v63, v197
	v_sub_f32_e32 v62, v62, v197
	v_sub_f32_e32 v61, v61, v197
	v_sub_f32_e32 v60, v60, v197
	v_sub_f32_e32 v67, v67, v197
	v_sub_f32_e32 v66, v66, v197
	v_sub_f32_e32 v65, v65, v197
	v_sub_f32_e32 v64, v64, v197
	v_sub_f32_e32 v87, v87, v197
	v_sub_f32_e32 v86, v86, v197
	v_sub_f32_e32 v85, v85, v197
	v_sub_f32_e32 v84, v84, v197

.LBB0_882:
	s_cmp_eq_u32 s99, 0
	s_cbranch_scc1 .Lq1_h2_stv
	s_waitcnt vmcnt(3)
	ds_write_b128 v211, v[28:31] offset:35840
	s_waitcnt vmcnt(2)
	ds_write_b128 v211, v[32:35] offset:35968
.Lq1_h2_stv:
	s_waitcnt vmcnt(1)
	ds_write_b128 v213, v[4:7] offset:17408
	s_waitcnt vmcnt(0)
	ds_write_b128 v213, v[12:15] offset:17536
	s_waitcnt lgkmcnt(0)
	s_barrier
	v_lshl_add_u64 v[202:203], v[202:203], 0, s[10:11]
	s_addk_i32 s87, 0x80
	s_mov_b32 s89, s88
	s_branch .LBB0_836
.Lq1_h2_pvonly:
	ds_read_b64_tr_b16 v[64:65], v215 offset:53248
	ds_read_b64_tr_b16 v[108:109], v215 offset:53280
	ds_read_b64_tr_b16 v[120:121], v215 offset:53312
	ds_read_b64_tr_b16 v[128:129], v215 offset:53344
	ds_read_b64_tr_b16 v[66:67], v215 offset:57856
	ds_read_b64_tr_b16 v[110:111], v215 offset:57888
	ds_read_b64_tr_b16 v[122:123], v215 offset:57920
	ds_read_b64_tr_b16 v[130:131], v215 offset:57952
	s_waitcnt lgkmcnt(3)
	v_mfma_f32_16x16x32_bf16 v[124:127], v[44:47], v[64:67], v[144:147]
	v_mfma_f32_16x16x32_bf16 v[64:67], v[92:95], v[64:67], v[140:143]
	s_waitcnt lgkmcnt(2)
	v_mfma_f32_16x16x32_bf16 v[100:103], v[44:47], v[108:111], v[148:151]
	v_mfma_f32_16x16x32_bf16 v[108:111], v[92:95], v[108:111], v[136:139]
	s_waitcnt lgkmcnt(1)
	v_mfma_f32_16x16x32_bf16 v[116:119], v[44:47], v[120:123], v[156:159]
	v_mfma_f32_16x16x32_bf16 v[96:99], v[92:95], v[120:123], v[152:155]
	s_waitcnt lgkmcnt(0)
	v_mfma_f32_16x16x32_bf16 v[104:107], v[44:47], v[128:131], v[164:167]
	v_mfma_f32_16x16x32_bf16 v[76:79], v[92:95], v[128:131], v[160:163]
	ds_read_b64_tr_b16 v[120:121], v215 offset:53376
	ds_read_b64_tr_b16 v[128:129], v215 offset:53408
	ds_read_b64_tr_b16 v[88:89], v215 offset:53440
	ds_read_b64_tr_b16 v[80:81], v215 offset:53472
	ds_read_b64_tr_b16 v[122:123], v215 offset:57984
	ds_read_b64_tr_b16 v[130:131], v215 offset:58016
	ds_read_b64_tr_b16 v[90:91], v215 offset:58048
	ds_read_b64_tr_b16 v[82:83], v215 offset:58080
	s_waitcnt lgkmcnt(3)
	v_mfma_f32_16x16x32_bf16 v[52:55], v[44:47], v[120:123], v[172:175]
	v_mfma_f32_16x16x32_bf16 v[68:71], v[92:95], v[120:123], v[168:171]
	s_waitcnt lgkmcnt(2)
	v_mfma_f32_16x16x32_bf16 v[48:51], v[44:47], v[128:131], v[176:179]
	v_mfma_f32_16x16x32_bf16 v[56:59], v[92:95], v[128:131], v[132:135]
	s_waitcnt lgkmcnt(1)
	v_mfma_f32_16x16x32_bf16 v[218:221], v[44:47], v[88:91], v[184:187]
	v_mfma_f32_16x16x32_bf16 v[222:225], v[92:95], v[88:91], v[180:183]
	s_waitcnt lgkmcnt(0)
	v_mfma_f32_16x16x32_bf16 v[226:229], v[44:47], v[80:83], v[192:195]
	v_mfma_f32_16x16x32_bf16 v[230:233], v[92:95], v[80:83], v[188:191]
	ds_read_b64_tr_b16 v[120:121], v215 offset:62464
	ds_read_b64_tr_b16 v[88:89], v215 offset:62496
	ds_read_b64_tr_b16 v[80:81], v215 offset:62528
	ds_read_b64_tr_b16 v[234:235], v215 offset:62560
	ds_read_b64_tr_b16 v[122:123], v216 offset:13824
	ds_read_b64_tr_b16 v[90:91], v216 offset:13856
	ds_read_b64_tr_b16 v[82:83], v216 offset:13888
	ds_read_b64_tr_b16 v[236:237], v216 offset:13920
	s_waitcnt lgkmcnt(3)
	v_mfma_f32_16x16x32_bf16 v[128:131], v[72:75], v[120:123], v[124:127]
	v_mfma_f32_16x16x32_bf16 v[120:123], v[112:115], v[120:123], v[64:67]
	s_waitcnt lgkmcnt(2)
	v_mfma_f32_16x16x32_bf16 v[124:127], v[72:75], v[88:91], v[100:103]
	v_mfma_f32_16x16x32_bf16 v[108:111], v[112:115], v[88:91], v[108:111]
	s_waitcnt lgkmcnt(1)
	v_mfma_f32_16x16x32_bf16 v[116:119], v[72:75], v[80:83], v[116:119]
	v_mfma_f32_16x16x32_bf16 v[100:103], v[112:115], v[80:83], v[96:99]
	s_waitcnt lgkmcnt(0)
	v_mfma_f32_16x16x32_bf16 v[104:107], v[72:75], v[234:237], v[104:107]
	v_mfma_f32_16x16x32_bf16 v[96:99], v[112:115], v[234:237], v[76:79]
	ds_read_b64_tr_b16 v[64:65], v215 offset:62592
	ds_read_b64_tr_b16 v[234:235], v215 offset:62624
	ds_read_b64_tr_b16 v[238:239], v215 offset:62656
	ds_read_b64_tr_b16 v[242:243], v215 offset:62688
	ds_read_b64_tr_b16 v[66:67], v216 offset:13952
	ds_read_b64_tr_b16 v[236:237], v216 offset:13984
	ds_read_b64_tr_b16 v[240:241], v216 offset:14016
	ds_read_b64_tr_b16 v[244:245], v216 offset:14048
	s_waitcnt lgkmcnt(3)
	v_mfma_f32_16x16x32_bf16 v[88:91], v[72:75], v[64:67], v[52:55]
	v_mfma_f32_16x16x32_bf16 v[76:79], v[112:115], v[64:67], v[68:71]
	s_waitcnt lgkmcnt(2)
	v_mfma_f32_16x16x32_bf16 v[80:83], v[72:75], v[234:237], v[48:51]
	v_mfma_f32_16x16x32_bf16 v[64:67], v[112:115], v[234:237], v[56:59]
	s_waitcnt lgkmcnt(1)
	v_mfma_f32_16x16x32_bf16 v[68:71], v[72:75], v[238:241], v[218:221]
	v_mfma_f32_16x16x32_bf16 v[52:55], v[112:115], v[238:241], v[222:225]
	s_waitcnt lgkmcnt(0)
	v_mfma_f32_16x16x32_bf16 v[56:59], v[72:75], v[242:245], v[226:229]
	v_mfma_f32_16x16x32_bf16 v[48:51], v[112:115], v[242:245], v[230:233]
	s_mov_b64 s[2:3], 0
	s_branch .LBB0_882
; template <bool SAMPLE> __device__ __forceinline__ void attn_unit16(const Ctx& c, LAS unsigned char* lds, int b, int h, int qb, int wave_s) {
;     ...
;     for (int j = 0; j < ntiles; j += 2) {
;         ITER16(j, pfa, pfb, 0, 1);
;         if (j + 1 < ntiles) ITER16(j + 1, pfb, pfa, 1, 0);
;     }
.Lq1_last:
	s_cmp_ge_u32 s89, s85
	s_cbranch_scc1 .Lq1_last_bar
	ds_read_b64_tr_b16 v[132:133], v215 offset:17408
	ds_read_b64_tr_b16 v[136:137], v215 offset:17440
	ds_read_b64_tr_b16 v[140:141], v215 offset:17472
	ds_read_b64_tr_b16 v[144:145], v215 offset:17504
	ds_read_b64_tr_b16 v[134:135], v215 offset:22016
	ds_read_b64_tr_b16 v[138:139], v215 offset:22048
	ds_read_b64_tr_b16 v[142:143], v215 offset:22080
	ds_read_b64_tr_b16 v[146:147], v215 offset:22112
	s_waitcnt lgkmcnt(3)
	v_mfma_f32_16x16x32_bf16 v[148:151], v[36:39], v[132:135], v[128:131]
	v_mfma_f32_16x16x32_bf16 v[132:135], v[60:63], v[132:135], v[120:123]
	s_waitcnt lgkmcnt(2)
	v_mfma_f32_16x16x32_bf16 v[152:155], v[36:39], v[136:139], v[124:127]
	v_mfma_f32_16x16x32_bf16 v[136:139], v[60:63], v[136:139], v[108:111]
	s_waitcnt lgkmcnt(1)
	v_mfma_f32_16x16x32_bf16 v[156:159], v[36:39], v[140:143], v[116:119]
	v_mfma_f32_16x16x32_bf16 v[160:163], v[60:63], v[140:143], v[100:103]
	s_waitcnt lgkmcnt(0)
	v_mfma_f32_16x16x32_bf16 v[164:167], v[36:39], v[144:147], v[104:107]
	v_mfma_f32_16x16x32_bf16 v[168:171], v[60:63], v[144:147], v[96:99]
	ds_read_b64_tr_b16 v[140:141], v215 offset:17536
	ds_read_b64_tr_b16 v[144:145], v215 offset:17568
	ds_read_b64_tr_b16 v[172:173], v215 offset:17600
	ds_read_b64_tr_b16 v[176:177], v215 offset:17632
	ds_read_b64_tr_b16 v[142:143], v215 offset:22144
	ds_read_b64_tr_b16 v[146:147], v215 offset:22176
	ds_read_b64_tr_b16 v[174:175], v215 offset:22208
	ds_read_b64_tr_b16 v[178:179], v215 offset:22240
	s_waitcnt lgkmcnt(3)
	v_mfma_f32_16x16x32_bf16 v[180:183], v[36:39], v[140:143], v[88:91]
	v_mfma_f32_16x16x32_bf16 v[184:187], v[60:63], v[140:143], v[76:79]
	s_waitcnt lgkmcnt(2)
	v_mfma_f32_16x16x32_bf16 v[188:191], v[36:39], v[144:147], v[80:83]
	v_mfma_f32_16x16x32_bf16 v[192:195], v[60:63], v[144:147], v[64:67]
	s_waitcnt lgkmcnt(1)
	v_mfma_f32_16x16x32_bf16 v[218:221], v[36:39], v[172:175], v[68:71]
	v_mfma_f32_16x16x32_bf16 v[222:225], v[60:63], v[172:175], v[52:55]
	s_waitcnt lgkmcnt(0)
	v_mfma_f32_16x16x32_bf16 v[226:229], v[36:39], v[176:179], v[56:59]
	v_mfma_f32_16x16x32_bf16 v[230:233], v[60:63], v[176:179], v[48:51]
	ds_read_b64_tr_b16 v[140:141], v215 offset:26624
	ds_read_b64_tr_b16 v[172:173], v215 offset:26656
	ds_read_b64_tr_b16 v[176:177], v215 offset:26688
	ds_read_b64_tr_b16 v[234:235], v215 offset:26720
	ds_read_b64_tr_b16 v[142:143], v215 offset:31232
	ds_read_b64_tr_b16 v[174:175], v215 offset:31264
	ds_read_b64_tr_b16 v[178:179], v215 offset:31296
	ds_read_b64_tr_b16 v[236:237], v215 offset:31328
	s_waitcnt lgkmcnt(3)
	v_mfma_f32_16x16x32_bf16 v[144:147], v[40:43], v[140:143], v[148:151]
	v_mfma_f32_16x16x32_bf16 v[140:143], v[84:87], v[140:143], v[132:135]
	s_waitcnt lgkmcnt(2)
	v_mfma_f32_16x16x32_bf16 v[148:151], v[40:43], v[172:175], v[152:155]
	v_mfma_f32_16x16x32_bf16 v[136:139], v[84:87], v[172:175], v[136:139]
	s_waitcnt lgkmcnt(1)
	v_mfma_f32_16x16x32_bf16 v[156:159], v[40:43], v[176:179], v[156:159]
	v_mfma_f32_16x16x32_bf16 v[152:155], v[84:87], v[176:179], v[160:163]
	s_waitcnt lgkmcnt(0)
	v_mfma_f32_16x16x32_bf16 v[164:167], v[40:43], v[234:237], v[164:167]
	v_mfma_f32_16x16x32_bf16 v[160:163], v[84:87], v[234:237], v[168:171]
	ds_read_b64_tr_b16 v[132:133], v215 offset:26752
	ds_read_b64_tr_b16 v[234:235], v215 offset:26784
	ds_read_b64_tr_b16 v[238:239], v215 offset:26816
	ds_read_b64_tr_b16 v[242:243], v215 offset:26848
	ds_read_b64_tr_b16 v[134:135], v215 offset:31360
	ds_read_b64_tr_b16 v[236:237], v215 offset:31392
	ds_read_b64_tr_b16 v[240:241], v215 offset:31424
	ds_read_b64_tr_b16 v[244:245], v215 offset:31456
	s_waitcnt lgkmcnt(3)
	v_mfma_f32_16x16x32_bf16 v[172:175], v[40:43], v[132:135], v[180:183]
	v_mfma_f32_16x16x32_bf16 v[168:171], v[84:87], v[132:135], v[184:187]
	s_waitcnt lgkmcnt(2)
	v_mfma_f32_16x16x32_bf16 v[176:179], v[40:43], v[234:237], v[188:191]
	v_mfma_f32_16x16x32_bf16 v[132:135], v[84:87], v[234:237], v[192:195]
	s_waitcnt lgkmcnt(1)
	v_mfma_f32_16x16x32_bf16 v[184:187], v[40:43], v[238:241], v[218:221]
	v_mfma_f32_16x16x32_bf16 v[180:183], v[84:87], v[238:241], v[222:225]
	s_waitcnt lgkmcnt(0)
	v_mfma_f32_16x16x32_bf16 v[192:195], v[40:43], v[242:245], v[226:229]
	v_mfma_f32_16x16x32_bf16 v[188:191], v[84:87], v[242:245], v[230:233]
	s_mov_b64 s[0:1], 0
	s_nop 7
	v_mov_b64_e32 v[128:129], v[144:145]
	v_mov_b64_e32 v[124:125], v[148:149]
	v_mov_b64_e32 v[116:117], v[156:157]
	v_mov_b64_e32 v[104:105], v[164:165]
	v_mov_b64_e32 v[88:89], v[172:173]
	v_mov_b64_e32 v[80:81], v[176:177]
	v_mov_b64_e32 v[68:69], v[184:185]
	v_mov_b64_e32 v[56:57], v[192:193]
	v_mov_b64_e32 v[120:121], v[140:141]
	v_mov_b64_e32 v[108:109], v[136:137]
	v_mov_b64_e32 v[100:101], v[152:153]
	v_mov_b64_e32 v[96:97], v[160:161]
	v_mov_b64_e32 v[76:77], v[168:169]
	v_mov_b64_e32 v[64:65], v[132:133]
	v_mov_b64_e32 v[52:53], v[180:181]
	v_mov_b64_e32 v[48:49], v[188:189]
	v_mov_b64_e32 v[130:131], v[146:147]
	v_mov_b64_e32 v[126:127], v[150:151]
	v_mov_b64_e32 v[118:119], v[158:159]
	v_mov_b64_e32 v[106:107], v[166:167]
	v_mov_b64_e32 v[90:91], v[174:175]
	v_mov_b64_e32 v[82:83], v[178:179]
	v_mov_b64_e32 v[70:71], v[186:187]
	v_mov_b64_e32 v[58:59], v[194:195]
	v_mov_b64_e32 v[122:123], v[142:143]
	v_mov_b64_e32 v[110:111], v[138:139]
	v_mov_b64_e32 v[102:103], v[154:155]
	v_mov_b64_e32 v[98:99], v[162:163]
	v_mov_b64_e32 v[78:79], v[170:171]
	v_mov_b64_e32 v[66:67], v[134:135]
	v_mov_b64_e32 v[54:55], v[182:183]
	v_mov_b64_e32 v[50:51], v[190:191]
.Lq1_last_bar:
	s_waitcnt lgkmcnt(0)
	s_barrier
	v_lshl_add_u64 v[202:203], v[202:203], 0, s[10:11]
	s_addk_i32 s87, 0x80

.LBB0_902:
	s_add_i32 s81, s82, 2
	s_cmp_lt_u32 s81, s61
	s_cbranch_scc0 .Lq2_last
	v_add_co_u32_e32 v2, vcc, 0xfbf00000, v202
	s_nop 1
	v_addc_co_u32_e32 v3, vcc, -1, v203, vcc
	global_load_dwordx4 v[28:31], v[2:3], off offset:-128
	global_load_dwordx4 v[32:35], v[2:3], off
	v_add_co_u32_e32 v2, vcc, 0xffffc000, v202
	s_nop 1
	v_addc_co_u32_e32 v3, vcc, -1, v203, vcc
	global_load_dwordx4 v[4:7], v[2:3], off offset:-128
	global_load_dwordx4 v[16:19], v[2:3], off
	ds_read_b128 v[44:47], v221 offset:35840
	ds_read_b128 v[56:59], v221 offset:35904
	ds_read_b128 v[88:91], v221 offset:40192
	ds_read_b128 v[96:99], v221 offset:40256
	ds_read_b128 v[132:135], v221 offset:44544
	ds_read_b128 v[148:151], v221 offset:44608
	ds_read_b128 v[136:139], v221 offset:48896
	ds_read_b128 v[152:155], v221 offset:48960
	s_waitcnt lgkmcnt(7)
	v_mfma_f32_16x16x32_bf16 v[140:143], v[44:47], v[8:11], 0
	v_mfma_f32_16x16x32_bf16 v[44:47], v[44:47], v[20:23], 0
	s_waitcnt lgkmcnt(5)
	v_mfma_f32_16x16x32_bf16 v[156:159], v[88:91], v[8:11], 0
	v_mfma_f32_16x16x32_bf16 v[88:91], v[88:91], v[20:23], 0
	s_waitcnt lgkmcnt(3)
	v_mfma_f32_16x16x32_bf16 v[160:163], v[132:135], v[8:11], 0
	v_mfma_f32_16x16x32_bf16 v[132:135], v[132:135], v[20:23], 0
	s_waitcnt lgkmcnt(1)
	v_mfma_f32_16x16x32_bf16 v[164:167], v[136:139], v[8:11], 0
	v_mfma_f32_16x16x32_bf16 v[168:171], v[136:139], v[20:23], 0
	v_mfma_f32_16x16x32_bf16 v[144:147], v[56:59], v[12:15], v[140:143]
	v_mfma_f32_16x16x32_bf16 v[136:139], v[56:59], v[24:27], v[44:47]
	v_mfma_f32_16x16x32_bf16 v[44:47], v[96:99], v[12:15], v[156:159]
	v_mfma_f32_16x16x32_bf16 v[88:91], v[96:99], v[24:27], v[88:91]
	v_mfma_f32_16x16x32_bf16 v[140:143], v[148:151], v[12:15], v[160:163]
	v_mfma_f32_16x16x32_bf16 v[132:135], v[148:151], v[24:27], v[132:135]
	s_waitcnt lgkmcnt(0)
	v_mfma_f32_16x16x32_bf16 v[56:59], v[152:155], v[12:15], v[164:167]
	v_mfma_f32_16x16x32_bf16 v[96:99], v[152:155], v[24:27], v[168:171]
	v_cmp_neq_f32_e32 vcc, 0, v196
	v_cmp_neq_f32_e64 s[0:1], 0, v197
	s_or_b64 vcc, vcc, s[0:1]
	s_cbranch_vccz .LBB0_925
	v_sub_f32_e32 v147, v147, v196
	v_sub_f32_e32 v146, v146, v196
	v_sub_f32_e32 v145, v145, v196
	v_sub_f32_e32 v144, v144, v196
	v_sub_f32_e32 v47, v47, v196
	v_sub_f32_e32 v46, v46, v196
	v_sub_f32_e32 v45, v45, v196
	v_sub_f32_e32 v44, v44, v196
	v_sub_f32_e32 v143, v143, v196
	v_sub_f32_e32 v142, v142, v196
	v_sub_f32_e32 v141, v141, v196
	v_sub_f32_e32 v140, v140, v196
	v_sub_f32_e32 v59, v59, v196
	v_sub_f32_e32 v58, v58, v196
	v_sub_f32_e32 v57, v57, v196
	v_sub_f32_e32 v56, v56, v196
	v_sub_f32_e32 v139, v139, v197
	v_sub_f32_e32 v138, v138, v197
	v_sub_f32_e32 v137, v137, v197
	v_sub_f32_e32 v136, v136, v197
	v_sub_f32_e32 v91, v91, v197
	v_sub_f32_e32 v90, v90, v197
	v_sub_f32_e32 v89, v89, v197
	v_sub_f32_e32 v88, v88, v197
	v_sub_f32_e32 v135, v135, v197
	v_sub_f32_e32 v134, v134, v197
	v_sub_f32_e32 v133, v133, v197
	v_sub_f32_e32 v132, v132, v197
	v_sub_f32_e32 v99, v99, v197
	v_sub_f32_e32 v98, v98, v197
	v_sub_f32_e32 v97, v97, v197
	v_sub_f32_e32 v96, v96, v197

.LBB0_932:
	s_waitcnt vmcnt(3)
	ds_write_b128 v219, v[28:31]
	s_waitcnt vmcnt(2)
	ds_write_b128 v219, v[32:35] offset:128
	s_waitcnt vmcnt(1)
	ds_write_b128 v225, v[4:7] offset:53248
	s_waitcnt vmcnt(0)
	ds_write_b128 v225, v[16:19] offset:53376
	s_waitcnt lgkmcnt(0)
	s_barrier
	s_cmp_lt_u32 s82, s56
	s_cselect_b32 s99, 1, 0
	s_cbranch_scc0 .Lq2_h2_nok
	v_add_co_u32_e32 v2, vcc, 0xfbf04000, v202
	s_nop 1
	v_addc_co_u32_e32 v3, vcc, -1, v203, vcc
	global_load_dwordx4 v[28:31], v[2:3], off offset:-128
	global_load_dwordx4 v[32:35], v[2:3], off
.Lq2_h2_nok:
	global_load_dwordx4 v[4:7], v[202:203], off offset:-128
	global_load_dwordx4 v[16:19], v[202:203], off
	s_cmp_ge_u32 s82, s60
	s_cbranch_scc1 .Lq2_h2_pvonly
	ds_read_b128 v[36:39], v221
	ds_read_b128 v[40:43], v221 offset:64
	ds_read_b128 v[48:51], v221 offset:4352
	ds_read_b128 v[76:79], v221 offset:4416
	ds_read_b128 v[72:75], v221 offset:8704
	ds_read_b128 v[120:123], v221 offset:8768
	ds_read_b128 v[116:119], v221 offset:13056
	ds_read_b128 v[108:111], v221 offset:13120
	s_waitcnt lgkmcnt(7)
	v_mfma_f32_16x16x32_bf16 v[124:127], v[36:39], v[8:11], 0
	v_mfma_f32_16x16x32_bf16 v[36:39], v[36:39], v[20:23], 0
	s_waitcnt lgkmcnt(5)
	v_mfma_f32_16x16x32_bf16 v[112:115], v[48:51], v[8:11], 0
	v_mfma_f32_16x16x32_bf16 v[48:51], v[48:51], v[20:23], 0
	s_waitcnt lgkmcnt(3)
	v_mfma_f32_16x16x32_bf16 v[100:103], v[72:75], v[8:11], 0
	v_mfma_f32_16x16x32_bf16 v[72:75], v[72:75], v[20:23], 0
	s_waitcnt lgkmcnt(1)
	v_mfma_f32_16x16x32_bf16 v[104:107], v[116:119], v[8:11], 0
	v_mfma_f32_16x16x32_bf16 v[84:87], v[116:119], v[20:23], 0
	v_mfma_f32_16x16x32_bf16 v[128:131], v[40:43], v[12:15], v[124:127]
	v_mfma_f32_16x16x32_bf16 v[116:119], v[40:43], v[24:27], v[36:39]
	v_mfma_f32_16x16x32_bf16 v[36:39], v[76:79], v[12:15], v[112:115]
	v_mfma_f32_16x16x32_bf16 v[48:51], v[76:79], v[24:27], v[48:51]
	v_mfma_f32_16x16x32_bf16 v[124:127], v[120:123], v[12:15], v[100:103]
	v_mfma_f32_16x16x32_bf16 v[72:75], v[120:123], v[24:27], v[72:75]
	s_waitcnt lgkmcnt(0)
	v_mfma_f32_16x16x32_bf16 v[40:43], v[108:111], v[12:15], v[104:107]
	v_mfma_f32_16x16x32_bf16 v[76:79], v[108:111], v[24:27], v[84:87]
	v_cmp_neq_f32_e32 vcc, 0, v196
	v_cmp_neq_f32_e64 s[2:3], 0, v197
	s_or_b64 vcc, vcc, s[2:3]
	s_cbranch_vccz .LBB0_941
	v_sub_f32_e32 v131, v131, v196
	v_sub_f32_e32 v130, v130, v196
	v_sub_f32_e32 v129, v129, v196
	v_sub_f32_e32 v128, v128, v196
	v_sub_f32_e32 v39, v39, v196
	v_sub_f32_e32 v38, v38, v196
	v_sub_f32_e32 v37, v37, v196
	v_sub_f32_e32 v36, v36, v196
	v_sub_f32_e32 v127, v127, v196
	v_sub_f32_e32 v126, v126, v196
	v_sub_f32_e32 v125, v125, v196
	v_sub_f32_e32 v124, v124, v196
	v_sub_f32_e32 v43, v43, v196
	v_sub_f32_e32 v42, v42, v196
	v_sub_f32_e32 v41, v41, v196
	v_sub_f32_e32 v40, v40, v196
	v_sub_f32_e32 v119, v119, v197
	v_sub_f32_e32 v118, v118, v197
	v_sub_f32_e32 v117, v117, v197
	v_sub_f32_e32 v116, v116, v197
	v_sub_f32_e32 v51, v51, v197
	v_sub_f32_e32 v50, v50, v197
	v_sub_f32_e32 v49, v49, v197
	v_sub_f32_e32 v48, v48, v197
	v_sub_f32_e32 v75, v75, v197
	v_sub_f32_e32 v74, v74, v197
	v_sub_f32_e32 v73, v73, v197
	v_sub_f32_e32 v72, v72, v197
	v_sub_f32_e32 v79, v79, v197
	v_sub_f32_e32 v78, v78, v197
	v_sub_f32_e32 v77, v77, v197
	v_sub_f32_e32 v76, v76, v197

.LBB0_948:
	s_cmp_eq_u32 s99, 0
	s_cbranch_scc1 .Lq2_h2_stv
	s_waitcnt vmcnt(3)
	ds_write_b128 v219, v[28:31] offset:35840
	s_waitcnt vmcnt(2)
	ds_write_b128 v219, v[32:35] offset:35968
.Lq2_h2_stv:
	s_waitcnt vmcnt(1)
	ds_write_b128 v220, v[4:7] offset:17408
	s_waitcnt vmcnt(0)
	ds_write_b128 v220, v[16:19] offset:17536
	s_waitcnt lgkmcnt(0)
	s_barrier
	v_lshl_add_u64 v[202:203], v[202:203], 0, s[10:11]
	s_addk_i32 s80, 0x80
	s_mov_b32 s82, s81
	s_branch .LBB0_902
.Lq2_h2_pvonly:
	ds_read_b64_tr_b16 v[72:73], v222 offset:53248
	ds_read_b64_tr_b16 v[116:117], v222 offset:53280
	ds_read_b64_tr_b16 v[124:125], v222 offset:53312
	ds_read_b64_tr_b16 v[128:129], v222 offset:53344
	ds_read_b64_tr_b16 v[74:75], v222 offset:57856
	ds_read_b64_tr_b16 v[118:119], v222 offset:57888
	ds_read_b64_tr_b16 v[126:127], v222 offset:57920
	ds_read_b64_tr_b16 v[130:131], v222 offset:57952
	s_waitcnt lgkmcnt(3)
	v_mfma_f32_16x16x32_bf16 v[120:123], v[44:47], v[72:75], v[144:147]
	v_mfma_f32_16x16x32_bf16 v[72:75], v[88:91], v[72:75], v[140:143]
	s_waitcnt lgkmcnt(2)
	v_mfma_f32_16x16x32_bf16 v[108:111], v[44:47], v[116:119], v[148:151]
	v_mfma_f32_16x16x32_bf16 v[116:119], v[88:91], v[116:119], v[136:139]
	s_waitcnt lgkmcnt(1)
	v_mfma_f32_16x16x32_bf16 v[112:115], v[44:47], v[124:127], v[156:159]
	v_mfma_f32_16x16x32_bf16 v[100:103], v[88:91], v[124:127], v[152:155]
	s_waitcnt lgkmcnt(0)
	v_mfma_f32_16x16x32_bf16 v[104:107], v[44:47], v[128:131], v[164:167]
	v_mfma_f32_16x16x32_bf16 v[84:87], v[88:91], v[128:131], v[160:163]
	ds_read_b64_tr_b16 v[124:125], v222 offset:53376
	ds_read_b64_tr_b16 v[128:129], v222 offset:53408
	ds_read_b64_tr_b16 v[92:93], v222 offset:53440
	ds_read_b64_tr_b16 v[80:81], v222 offset:53472
	ds_read_b64_tr_b16 v[126:127], v222 offset:57984
	ds_read_b64_tr_b16 v[130:131], v222 offset:58016
	ds_read_b64_tr_b16 v[94:95], v222 offset:58048
	ds_read_b64_tr_b16 v[82:83], v222 offset:58080
	s_waitcnt lgkmcnt(3)
	v_mfma_f32_16x16x32_bf16 v[64:67], v[44:47], v[124:127], v[172:175]
	v_mfma_f32_16x16x32_bf16 v[68:71], v[88:91], v[124:127], v[168:171]
	s_waitcnt lgkmcnt(2)
	v_mfma_f32_16x16x32_bf16 v[52:55], v[44:47], v[128:131], v[176:179]
	v_mfma_f32_16x16x32_bf16 v[60:63], v[88:91], v[128:131], v[132:135]
	s_waitcnt lgkmcnt(1)
	v_mfma_f32_16x16x32_bf16 v[226:229], v[44:47], v[92:95], v[184:187]
	v_mfma_f32_16x16x32_bf16 v[230:233], v[88:91], v[92:95], v[180:183]
	s_waitcnt lgkmcnt(0)
	v_mfma_f32_16x16x32_bf16 v[234:237], v[44:47], v[80:83], v[192:195]
	v_mfma_f32_16x16x32_bf16 v[238:241], v[88:91], v[80:83], v[188:191]
	ds_read_b64_tr_b16 v[124:125], v222 offset:62464
	ds_read_b64_tr_b16 v[92:93], v222 offset:62496
	ds_read_b64_tr_b16 v[80:81], v222 offset:62528
	ds_read_b64_tr_b16 v[242:243], v222 offset:62560
	ds_read_b64_tr_b16 v[126:127], v223 offset:13824
	ds_read_b64_tr_b16 v[94:95], v223 offset:13856
	ds_read_b64_tr_b16 v[82:83], v223 offset:13888
	ds_read_b64_tr_b16 v[244:245], v223 offset:13920
	s_waitcnt lgkmcnt(3)
	v_mfma_f32_16x16x32_bf16 v[128:131], v[56:59], v[124:127], v[120:123]
	v_mfma_f32_16x16x32_bf16 v[124:127], v[96:99], v[124:127], v[72:75]
	s_waitcnt lgkmcnt(2)
	v_mfma_f32_16x16x32_bf16 v[120:123], v[56:59], v[92:95], v[108:111]
	v_mfma_f32_16x16x32_bf16 v[116:119], v[96:99], v[92:95], v[116:119]
	s_waitcnt lgkmcnt(1)
	v_mfma_f32_16x16x32_bf16 v[112:115], v[56:59], v[80:83], v[112:115]
	v_mfma_f32_16x16x32_bf16 v[108:111], v[96:99], v[80:83], v[100:103]
	s_waitcnt lgkmcnt(0)
	v_mfma_f32_16x16x32_bf16 v[104:107], v[56:59], v[242:245], v[104:107]
	v_mfma_f32_16x16x32_bf16 v[100:103], v[96:99], v[242:245], v[84:87]
	ds_read_b64_tr_b16 v[72:73], v222 offset:62592
	ds_read_b64_tr_b16 v[242:243], v222 offset:62624
	ds_read_b64_tr_b16 v[246:247], v222 offset:62656
	ds_read_b64_tr_b16 v[250:251], v222 offset:62688
	ds_read_b64_tr_b16 v[74:75], v223 offset:13952
	ds_read_b64_tr_b16 v[244:245], v223 offset:13984
	ds_read_b64_tr_b16 v[248:249], v223 offset:14016
	ds_read_b64_tr_b16 v[252:253], v223 offset:14048
	s_waitcnt lgkmcnt(3)
	v_mfma_f32_16x16x32_bf16 v[92:95], v[56:59], v[72:75], v[64:67]
	v_mfma_f32_16x16x32_bf16 v[84:87], v[96:99], v[72:75], v[68:71]
	s_waitcnt lgkmcnt(2)
	v_mfma_f32_16x16x32_bf16 v[80:83], v[56:59], v[242:245], v[52:55]
	v_mfma_f32_16x16x32_bf16 v[72:75], v[96:99], v[242:245], v[60:63]
	s_waitcnt lgkmcnt(1)
	v_mfma_f32_16x16x32_bf16 v[68:71], v[56:59], v[246:249], v[226:229]
	v_mfma_f32_16x16x32_bf16 v[64:67], v[96:99], v[246:249], v[230:233]
	s_waitcnt lgkmcnt(0)
	v_mfma_f32_16x16x32_bf16 v[60:63], v[56:59], v[250:253], v[234:237]
	v_mfma_f32_16x16x32_bf16 v[52:55], v[96:99], v[250:253], v[238:241]
	s_mov_b64 s[2:3], 0
	s_branch .LBB0_948
; template <bool SAMPLE> __device__ __forceinline__ void attn_unit16(const Ctx& c, LAS unsigned char* lds, int b, int h, int qb, int wave_s) {
;     ...
;     for (int j = 0; j < ntiles; j += 2) {
;         ITER16(j, pfa, pfb, 0, 1);
;         if (j + 1 < ntiles) ITER16(j + 1, pfb, pfa, 1, 0);
;     }
.Lq2_last:
	s_cmp_ge_u32 s82, s62
	s_cbranch_scc1 .Lq2_last_bar
	ds_read_b64_tr_b16 v[132:133], v222 offset:17408
	ds_read_b64_tr_b16 v[136:137], v222 offset:17440
	ds_read_b64_tr_b16 v[140:141], v222 offset:17472
	ds_read_b64_tr_b16 v[144:145], v222 offset:17504
	ds_read_b64_tr_b16 v[134:135], v222 offset:22016
	ds_read_b64_tr_b16 v[138:139], v222 offset:22048
	ds_read_b64_tr_b16 v[142:143], v222 offset:22080
	ds_read_b64_tr_b16 v[146:147], v222 offset:22112
	s_waitcnt lgkmcnt(3)
	v_mfma_f32_16x16x32_bf16 v[148:151], v[36:39], v[132:135], v[128:131]
	v_mfma_f32_16x16x32_bf16 v[132:135], v[48:51], v[132:135], v[124:127]
	s_waitcnt lgkmcnt(2)
	v_mfma_f32_16x16x32_bf16 v[152:155], v[36:39], v[136:139], v[120:123]
	v_mfma_f32_16x16x32_bf16 v[136:139], v[48:51], v[136:139], v[116:119]
	s_waitcnt lgkmcnt(1)
	v_mfma_f32_16x16x32_bf16 v[156:159], v[36:39], v[140:143], v[112:115]
	v_mfma_f32_16x16x32_bf16 v[160:163], v[48:51], v[140:143], v[108:111]
	s_waitcnt lgkmcnt(0)
	v_mfma_f32_16x16x32_bf16 v[164:167], v[36:39], v[144:147], v[104:107]
	v_mfma_f32_16x16x32_bf16 v[168:171], v[48:51], v[144:147], v[100:103]
	ds_read_b64_tr_b16 v[140:141], v222 offset:17536
	ds_read_b64_tr_b16 v[144:145], v222 offset:17568
	ds_read_b64_tr_b16 v[172:173], v222 offset:17600
	ds_read_b64_tr_b16 v[176:177], v222 offset:17632
	ds_read_b64_tr_b16 v[142:143], v222 offset:22144
	ds_read_b64_tr_b16 v[146:147], v222 offset:22176
	ds_read_b64_tr_b16 v[174:175], v222 offset:22208
	ds_read_b64_tr_b16 v[178:179], v222 offset:22240
	s_waitcnt lgkmcnt(3)
	v_mfma_f32_16x16x32_bf16 v[180:183], v[36:39], v[140:143], v[92:95]
	v_mfma_f32_16x16x32_bf16 v[184:187], v[48:51], v[140:143], v[84:87]
	s_waitcnt lgkmcnt(2)
	v_mfma_f32_16x16x32_bf16 v[188:191], v[36:39], v[144:147], v[80:83]
	v_mfma_f32_16x16x32_bf16 v[192:195], v[48:51], v[144:147], v[72:75]
	s_waitcnt lgkmcnt(1)
	v_mfma_f32_16x16x32_bf16 v[226:229], v[36:39], v[172:175], v[68:71]
	v_mfma_f32_16x16x32_bf16 v[230:233], v[48:51], v[172:175], v[64:67]
	s_waitcnt lgkmcnt(0)
	v_mfma_f32_16x16x32_bf16 v[234:237], v[36:39], v[176:179], v[60:63]
	v_mfma_f32_16x16x32_bf16 v[238:241], v[48:51], v[176:179], v[52:55]
	ds_read_b64_tr_b16 v[140:141], v222 offset:26624
	ds_read_b64_tr_b16 v[172:173], v222 offset:26656
	ds_read_b64_tr_b16 v[176:177], v222 offset:26688
	ds_read_b64_tr_b16 v[242:243], v222 offset:26720
	ds_read_b64_tr_b16 v[142:143], v222 offset:31232
	ds_read_b64_tr_b16 v[174:175], v222 offset:31264
	ds_read_b64_tr_b16 v[178:179], v222 offset:31296
	ds_read_b64_tr_b16 v[244:245], v222 offset:31328
	s_waitcnt lgkmcnt(3)
	v_mfma_f32_16x16x32_bf16 v[144:147], v[40:43], v[140:143], v[148:151]
	v_mfma_f32_16x16x32_bf16 v[140:143], v[76:79], v[140:143], v[132:135]
	s_waitcnt lgkmcnt(2)
	v_mfma_f32_16x16x32_bf16 v[148:151], v[40:43], v[172:175], v[152:155]
	v_mfma_f32_16x16x32_bf16 v[136:139], v[76:79], v[172:175], v[136:139]
	s_waitcnt lgkmcnt(1)
	v_mfma_f32_16x16x32_bf16 v[156:159], v[40:43], v[176:179], v[156:159]
	v_mfma_f32_16x16x32_bf16 v[152:155], v[76:79], v[176:179], v[160:163]
	s_waitcnt lgkmcnt(0)
	v_mfma_f32_16x16x32_bf16 v[164:167], v[40:43], v[242:245], v[164:167]
	v_mfma_f32_16x16x32_bf16 v[160:163], v[76:79], v[242:245], v[168:171]
	ds_read_b64_tr_b16 v[132:133], v222 offset:26752
	ds_read_b64_tr_b16 v[242:243], v222 offset:26784
	ds_read_b64_tr_b16 v[246:247], v222 offset:26816
	ds_read_b64_tr_b16 v[250:251], v222 offset:26848
	ds_read_b64_tr_b16 v[134:135], v222 offset:31360
	ds_read_b64_tr_b16 v[244:245], v222 offset:31392
	ds_read_b64_tr_b16 v[248:249], v222 offset:31424
	ds_read_b64_tr_b16 v[252:253], v222 offset:31456
	s_waitcnt lgkmcnt(3)
	v_mfma_f32_16x16x32_bf16 v[172:175], v[40:43], v[132:135], v[180:183]
	v_mfma_f32_16x16x32_bf16 v[168:171], v[76:79], v[132:135], v[184:187]
	s_waitcnt lgkmcnt(2)
	v_mfma_f32_16x16x32_bf16 v[176:179], v[40:43], v[242:245], v[188:191]
	v_mfma_f32_16x16x32_bf16 v[132:135], v[76:79], v[242:245], v[192:195]
	s_waitcnt lgkmcnt(1)
	v_mfma_f32_16x16x32_bf16 v[184:187], v[40:43], v[246:249], v[226:229]
	v_mfma_f32_16x16x32_bf16 v[180:183], v[76:79], v[246:249], v[230:233]
	s_waitcnt lgkmcnt(0)
	v_mfma_f32_16x16x32_bf16 v[192:195], v[40:43], v[250:253], v[234:237]
	v_mfma_f32_16x16x32_bf16 v[188:191], v[76:79], v[250:253], v[238:241]
	s_mov_b64 s[0:1], 0
	s_nop 7
	v_mov_b64_e32 v[128:129], v[144:145]
	v_mov_b64_e32 v[120:121], v[148:149]
	v_mov_b64_e32 v[112:113], v[156:157]
	v_mov_b64_e32 v[104:105], v[164:165]
	v_mov_b64_e32 v[92:93], v[172:173]
	v_mov_b64_e32 v[80:81], v[176:177]
	v_mov_b64_e32 v[68:69], v[184:185]
	v_mov_b64_e32 v[60:61], v[192:193]
	v_mov_b64_e32 v[124:125], v[140:141]
	v_mov_b64_e32 v[116:117], v[136:137]
	v_mov_b64_e32 v[108:109], v[152:153]
	v_mov_b64_e32 v[100:101], v[160:161]
	v_mov_b64_e32 v[84:85], v[168:169]
	v_mov_b64_e32 v[72:73], v[132:133]
	v_mov_b64_e32 v[64:65], v[180:181]
	v_mov_b64_e32 v[52:53], v[188:189]
	v_mov_b64_e32 v[130:131], v[146:147]
	v_mov_b64_e32 v[122:123], v[150:151]
	v_mov_b64_e32 v[114:115], v[158:159]
	v_mov_b64_e32 v[106:107], v[166:167]
	v_mov_b64_e32 v[94:95], v[174:175]
	v_mov_b64_e32 v[82:83], v[178:179]
	v_mov_b64_e32 v[70:71], v[186:187]
	v_mov_b64_e32 v[62:63], v[194:195]
	v_mov_b64_e32 v[126:127], v[142:143]
	v_mov_b64_e32 v[118:119], v[138:139]
	v_mov_b64_e32 v[110:111], v[154:155]
	v_mov_b64_e32 v[102:103], v[162:163]
	v_mov_b64_e32 v[86:87], v[170:171]
	v_mov_b64_e32 v[74:75], v[134:135]
	v_mov_b64_e32 v[66:67], v[182:183]
	v_mov_b64_e32 v[54:55], v[190:191]
.Lq2_last_bar:
	s_waitcnt lgkmcnt(0)
	s_barrier
	v_lshl_add_u64 v[202:203], v[202:203], 0, s[10:11]
	s_addk_i32 s80, 0x80

; #define LAS __attribute__((address_space(3)))
; __global__ void __launch_bounds__(512, 2) hybrid_fwd(Ctx c) {
;     extern __shared__ __attribute__((aligned(16))) unsigned char lds_raw[];
;     LAS unsigned char* lds = (LAS unsigned char*)lds_raw;
	.amdhsa_kernel _Z10hybrid_fwd3Ctx
		.amdhsa_group_segment_fixed_size 0
		.amdhsa_private_segment_fixed_size 0
		.amdhsa_kernarg_size 440
		.amdhsa_user_sgpr_count 2
		.amdhsa_user_sgpr_dispatch_ptr 0
		.amdhsa_user_sgpr_queue_ptr 0
		.amdhsa_user_sgpr_kernarg_segment_ptr 1
		.amdhsa_user_sgpr_dispatch_id 0
		.amdhsa_user_sgpr_kernarg_preload_length 0
		.amdhsa_user_sgpr_kernarg_preload_offset 0
		.amdhsa_user_sgpr_private_segment_size 0
		.amdhsa_uses_dynamic_stack 0
		.amdhsa_enable_private_segment 0
		.amdhsa_system_sgpr_workgroup_id_x 1
		.amdhsa_system_sgpr_workgroup_id_y 0
		.amdhsa_system_sgpr_workgroup_id_z 0
		.amdhsa_system_sgpr_workgroup_info 0
		.amdhsa_system_vgpr_workitem_id 2
		.amdhsa_next_free_vgpr 256
		.amdhsa_next_free_sgpr 100
		.amdhsa_accum_offset 256
		.amdhsa_reserve_vcc 1
		.amdhsa_float_round_mode_32 0
		.amdhsa_float_round_mode_16_64 0
		.amdhsa_float_denorm_mode_32 3
		.amdhsa_float_denorm_mode_16_64 3
		.amdhsa_dx10_clamp 1
		.amdhsa_ieee_mode 1
		.amdhsa_fp16_overflow 0
		.amdhsa_tg_split 0
		.amdhsa_exception_fp_ieee_invalid_op 0
		.amdhsa_exception_fp_denorm_src 0
		.amdhsa_exception_fp_ieee_div_zero 0
		.amdhsa_exception_fp_ieee_overflow 0
		.amdhsa_exception_fp_ieee_underflow 0
		.amdhsa_exception_fp_ieee_inexact 0
		.amdhsa_exception_int_div_zero 0
	.end_amdhsa_kernel

; #define LAS __attribute__((address_space(3)))
; __global__ void __launch_bounds__(512, 2) hybrid_fwd(Ctx c) {
;     extern __shared__ __attribute__((aligned(16))) unsigned char lds_raw[];
;     LAS unsigned char* lds = (LAS unsigned char*)lds_raw;
amdhsa.kernels:
  - .agpr_count:     0
    .args:
      - .offset:         0
        .size:           184
        .value_kind:     by_value
      - .offset:         184
        .size:           4
        .value_kind:     hidden_block_count_x
      - .offset:         188
        .size:           4
        .value_kind:     hidden_block_count_y
      - .offset:         192
        .size:           4
        .value_kind:     hidden_block_count_z
      - .offset:         196
        .size:           2
        .value_kind:     hidden_group_size_x
      - .offset:         198
        .size:           2
        .value_kind:     hidden_group_size_y
      - .offset:         200
        .size:           2
        .value_kind:     hidden_group_size_z
      - .offset:         202
        .size:           2
        .value_kind:     hidden_remainder_x
      - .offset:         204
        .size:           2
        .value_kind:     hidden_remainder_y
      - .offset:         206
        .size:           2
        .value_kind:     hidden_remainder_z
      - .offset:         224
        .size:           8
        .value_kind:     hidden_global_offset_x
      - .offset:         232
        .size:           8
        .value_kind:     hidden_global_offset_y
      - .offset:         240
        .size:           8
        .value_kind:     hidden_global_offset_z
      - .offset:         248
        .size:           2
        .value_kind:     hidden_grid_dims
      - .offset:         272
        .size:           8
        .value_kind:     hidden_multigrid_sync_arg
      - .offset:         304
        .size:           4
        .value_kind:     hidden_dynamic_lds_size
    .group_segment_fixed_size: 0
    .kernarg_segment_align: 8
    .kernarg_segment_size: 440
    .language:       OpenCL C
    .language_version:
      - 2
      - 0
    .max_flat_workgroup_size: 512
    .name:           _Z10hybrid_fwd3Ctx
    .private_segment_fixed_size: 0
    .sgpr_count:     106
    .sgpr_spill_count: 33
    .symbol:         _Z10hybrid_fwd3Ctx.kd
    .uniform_work_group_size: 1
    .uses_dynamic_stack: false
    .vgpr_count:     256
    .vgpr_spill_count: 0
    .wavefront_size: 64
